# v50 + GEMM tile headers zero the 128 accumulators with 64 v_mov_b64 instead of 128 v_mov_b32 (bf16 in-proj, fp8 in-proj, out-proj)
# speedup vs baseline: 1.0084x; 1.0003x over previous
;     __device__ bool next(int i, Unit& u) const { return i == 0 && base.next(round, u); }
; template <class Epi, class Sched, bool ALIGN_EPI = false, bool SP2 = false, bool F8 = false>
; __device__ __forceinline__ void gemm_phase(PG8_LAS unsigned char* lds, const Gemm g, const Sched& S, const Epi& E) {
;     ...
;         const bool has_next = S.next(ui + 1, nxt);
;         const char* nA = has_next ? (const char*)g.A + (size_t)nxt.pm * tstep : cA; const char* nB = has_next ? (const char*)g.Bt + (size_t)nxt.pn * tstep : cB;
;     ...
; #pragma unroll
;         for (int a = 0; a < 2; ++a)
; #pragma unroll
;             for (int b = 0; b < 2; ++b)
; #pragma unroll
;                 for (int m = 0; m < 4; ++m)
; #pragma unroll
;                     for (int n = 0; n < 2; ++n) acc[a][b][m][n] = (f32x4){0.f, 0.f, 0.f, 0.f};
.LBB0_125:
	s_ashr_i32 s31, s30, 31
	s_lshl_b64 s[34:35], s[30:31], 19
	s_add_u32 s34, s82, s34
	s_addc_u32 s35, s83, s35
	s_and_b64 s[36:37], s[0:1], exec
	s_cselect_b32 s5, s35, s41
	s_cselect_b32 s31, s34, s40
	s_ashr_i32 s29, s28, 31
	s_lshl_b64 s[36:37], s[28:29], 19
	s_add_u32 s36, s25, s36
	s_addc_u32 s37, s46, s37
	s_and_b64 s[44:45], s[0:1], exec
	s_cselect_b32 s29, s37, s43
	s_cselect_b32 s61, s36, s42
	s_add_u32 s40, s40, 0x60080
	s_addc_u32 s41, s41, 0
	s_add_u32 s62, s42, 0x100
	s_addc_u32 s63, s43, 0
	s_mov_b32 s64, -2
	v_mov_b64_e32 v[8:9], 0
	v_mov_b64_e32 v[10:11], 0
	v_mov_b64_e32 v[12:13], 0
	v_mov_b64_e32 v[14:15], 0
	v_mov_b64_e32 v[24:25], 0
	v_mov_b64_e32 v[26:27], 0
	v_mov_b64_e32 v[28:29], 0
	v_mov_b64_e32 v[30:31], 0
	v_mov_b64_e32 v[40:41], 0
	v_mov_b64_e32 v[42:43], 0
	v_mov_b64_e32 v[44:45], 0
	v_mov_b64_e32 v[46:47], 0
	v_mov_b64_e32 v[56:57], 0
	v_mov_b64_e32 v[58:59], 0
	v_mov_b64_e32 v[60:61], 0
	v_mov_b64_e32 v[62:63], 0
	v_mov_b64_e32 v[4:5], 0
	v_mov_b64_e32 v[6:7], 0
	v_mov_b64_e32 v[0:1], 0
	v_mov_b64_e32 v[2:3], 0
	v_mov_b64_e32 v[16:17], 0
	v_mov_b64_e32 v[18:19], 0
	v_mov_b64_e32 v[20:21], 0
	v_mov_b64_e32 v[22:23], 0
	v_mov_b64_e32 v[32:33], 0
	v_mov_b64_e32 v[34:35], 0
	v_mov_b64_e32 v[36:37], 0
	v_mov_b64_e32 v[38:39], 0
	v_mov_b64_e32 v[48:49], 0
	v_mov_b64_e32 v[50:51], 0
	v_mov_b64_e32 v[52:53], 0
	v_mov_b64_e32 v[54:55], 0
	v_mov_b64_e32 v[72:73], 0
	v_mov_b64_e32 v[74:75], 0
	v_mov_b64_e32 v[76:77], 0
	v_mov_b64_e32 v[78:79], 0
	v_mov_b64_e32 v[88:89], 0
	v_mov_b64_e32 v[90:91], 0
	v_mov_b64_e32 v[100:101], 0
	v_mov_b64_e32 v[102:103], 0
	v_mov_b64_e32 v[120:121], 0
	v_mov_b64_e32 v[122:123], 0
	v_mov_b64_e32 v[124:125], 0
	v_mov_b64_e32 v[126:127], 0
	v_mov_b64_e32 v[136:137], 0
	v_mov_b64_e32 v[138:139], 0
	v_mov_b64_e32 v[140:141], 0
	v_mov_b64_e32 v[142:143], 0
	v_mov_b64_e32 v[64:65], 0
	v_mov_b64_e32 v[66:67], 0
	v_mov_b64_e32 v[68:69], 0
	v_mov_b64_e32 v[70:71], 0
	v_mov_b64_e32 v[80:81], 0
	v_mov_b64_e32 v[82:83], 0
	v_mov_b64_e32 v[84:85], 0
	v_mov_b64_e32 v[86:87], 0
	v_mov_b64_e32 v[112:113], 0
	v_mov_b64_e32 v[114:115], 0
	v_mov_b64_e32 v[116:117], 0
	v_mov_b64_e32 v[118:119], 0
	v_mov_b64_e32 v[128:129], 0
	v_mov_b64_e32 v[130:131], 0
	v_mov_b64_e32 v[132:133], 0
	v_mov_b64_e32 v[134:135], 0
	v_add_u32_e32 v212, s6, v154
	v_add_u32_e32 v213, s8, v154
	v_add_u32_e32 v214, s10, v154
	v_add_u32_e32 v215, s6, v145
	v_add_u32_e32 v216, s8, v145
	v_add_u32_e32 v217, s10, v145
	v_add_u32_e32 v218, s14, v154
	v_add_u32_e32 v219, s16, v154
	v_add_u32_e32 v220, s18, v154
	v_add_u32_e32 v221, s20, v154
	v_add_u32_e32 v222, s14, v145
	v_add_u32_e32 v223, s16, v145

; template <class Epi, class Sched, bool ALIGN_EPI = false, bool SP2 = false, bool F8 = false>
; __device__ __forceinline__ void gemm_phase(PG8_LAS unsigned char* lds, const Gemm g, const Sched& S, const Epi& E) {
;     ...
;     f32x4 acc[2][2][4][2];
; #pragma unroll
;     for (int a = 0; a < 2; ++a)
; #pragma unroll
;         for (int b = 0; b < 2; ++b)
; #pragma unroll
;             for (int m = 0; m < 4; ++m)
; #pragma unroll
;                 for (int n = 0; n < 2; ++n) acc[a][b][m][n] = (f32x4){0.f, 0.f, 0.f, 0.f};
;     ...
; #pragma unroll
;         for (int a = 0; a < 2; ++a)
; #pragma unroll
;             for (int b = 0; b < 2; ++b)
; #pragma unroll
;                 for (int m = 0; m < 4; ++m)
; #pragma unroll
;                     for (int n = 0; n < 2; ++n) acc[a][b][m][n] = (f32x4){0.f, 0.f, 0.f, 0.f};
;         cur = nxt; cA = nA; cB = nB; ++ui;
.LBB0_177:
	s_andn2_b64 vcc, exec, s[16:17]
	v_mov_b64_e32 v[122:123], 0
	v_mov_b64_e32 v[120:121], 0
	v_mov_b64_e32 v[126:127], 0
	v_mov_b64_e32 v[124:125], 0
	v_mov_b64_e32 v[110:111], 0
	v_mov_b64_e32 v[108:109], 0
	v_mov_b64_e32 v[106:107], 0
	v_mov_b64_e32 v[104:105], 0
	v_mov_b64_e32 v[94:95], 0
	v_mov_b64_e32 v[92:93], 0
	v_mov_b64_e32 v[90:91], 0
	v_mov_b64_e32 v[88:89], 0
	v_mov_b64_e32 v[78:79], 0
	v_mov_b64_e32 v[76:77], 0
	v_mov_b64_e32 v[74:75], 0
	v_mov_b64_e32 v[72:73], 0
	v_mov_b64_e32 v[118:119], 0
	v_mov_b64_e32 v[116:117], 0
	v_mov_b64_e32 v[114:115], 0
	v_mov_b64_e32 v[112:113], 0
	v_mov_b64_e32 v[102:103], 0
	v_mov_b64_e32 v[100:101], 0
	v_mov_b64_e32 v[98:99], 0
	v_mov_b64_e32 v[96:97], 0
	v_mov_b64_e32 v[86:87], 0
	v_mov_b64_e32 v[84:85], 0
	v_mov_b64_e32 v[82:83], 0
	v_mov_b64_e32 v[80:81], 0
	v_mov_b64_e32 v[70:71], 0
	v_mov_b64_e32 v[68:69], 0
	v_mov_b64_e32 v[66:67], 0
	v_mov_b64_e32 v[64:65], 0
	v_mov_b64_e32 v[62:63], 0
	v_mov_b64_e32 v[60:61], 0
	v_mov_b64_e32 v[58:59], 0
	v_mov_b64_e32 v[56:57], 0
	v_mov_b64_e32 v[46:47], 0
	v_mov_b64_e32 v[44:45], 0
	v_mov_b64_e32 v[42:43], 0
	v_mov_b64_e32 v[40:41], 0
	v_mov_b64_e32 v[30:31], 0
	v_mov_b64_e32 v[28:29], 0
	v_mov_b64_e32 v[26:27], 0
	v_mov_b64_e32 v[24:25], 0
	v_mov_b64_e32 v[14:15], 0
	v_mov_b64_e32 v[12:13], 0
	v_mov_b64_e32 v[10:11], 0
	v_mov_b64_e32 v[8:9], 0
	v_mov_b64_e32 v[54:55], 0
	v_mov_b64_e32 v[52:53], 0
	v_mov_b64_e32 v[50:51], 0
	v_mov_b64_e32 v[48:49], 0
	v_mov_b64_e32 v[38:39], 0
	v_mov_b64_e32 v[36:37], 0
	v_mov_b64_e32 v[34:35], 0
	v_mov_b64_e32 v[32:33], 0
	v_mov_b64_e32 v[22:23], 0
	v_mov_b64_e32 v[20:21], 0
	v_mov_b64_e32 v[18:19], 0
	v_mov_b64_e32 v[16:17], 0
	v_mov_b64_e32 v[6:7], 0
	v_mov_b64_e32 v[4:5], 0
	v_mov_b64_e32 v[2:3], 0
	v_mov_b64_e32 v[0:1], 0
	s_cbranch_vccnz .LBB0_181
	s_add_u32 s72, s34, 0x80
	s_addc_u32 s73, s35, 0
	s_add_u32 s74, s30, 0x100
	v_mov_b32_e32 v0, 0
	s_mov_b64 vcc, s[82:83]
	s_addc_u32 s75, s31, 0
	s_mov_b32 s30, 0
	v_mov_b32_e32 v1, v0
	v_mov_b32_e32 v2, v0
	v_mov_b32_e32 v3, v0
	v_mov_b32_e32 v4, v0
	v_mov_b32_e32 v5, v0
	v_mov_b32_e32 v6, v0
	v_mov_b32_e32 v7, v0
	v_mov_b32_e32 v16, v0
	v_mov_b32_e32 v17, v0
	v_mov_b32_e32 v18, v0
	v_mov_b32_e32 v19, v0
	v_mov_b32_e32 v20, v0
	v_mov_b32_e32 v21, v0
	v_mov_b32_e32 v22, v0
	v_mov_b32_e32 v23, v0
	v_mov_b32_e32 v32, v0
	v_mov_b32_e32 v33, v0
	v_mov_b32_e32 v34, v0
	v_mov_b32_e32 v35, v0
	v_mov_b32_e32 v36, v0
	v_mov_b32_e32 v37, v0
	v_mov_b32_e32 v38, v0
	v_mov_b32_e32 v39, v0
	v_mov_b32_e32 v48, v0
	v_mov_b32_e32 v49, v0
	v_mov_b32_e32 v50, v0
	v_mov_b32_e32 v51, v0
	v_mov_b32_e32 v52, v0
	v_mov_b32_e32 v53, v0
	v_mov_b32_e32 v54, v0
	v_mov_b32_e32 v55, v0
	v_mov_b32_e32 v8, v0
	v_mov_b32_e32 v9, v0
	v_mov_b32_e32 v10, v0
	v_mov_b32_e32 v11, v0
	v_mov_b32_e32 v12, v0
	v_mov_b32_e32 v13, v0
	v_mov_b32_e32 v14, v0
	v_mov_b32_e32 v15, v0
	v_mov_b32_e32 v24, v0
	v_mov_b32_e32 v25, v0
	v_mov_b32_e32 v26, v0
	v_mov_b32_e32 v27, v0
	v_mov_b32_e32 v28, v0
	v_mov_b32_e32 v29, v0
	v_mov_b32_e32 v30, v0
	v_mov_b32_e32 v31, v0
	v_mov_b32_e32 v40, v0
	v_mov_b32_e32 v41, v0
	v_mov_b32_e32 v42, v0
	v_mov_b32_e32 v43, v0
	v_mov_b32_e32 v44, v0
	v_mov_b32_e32 v45, v0
	v_mov_b32_e32 v46, v0
	v_mov_b32_e32 v47, v0
	v_mov_b32_e32 v56, v0
	v_mov_b32_e32 v57, v0
	v_mov_b32_e32 v58, v0
	v_mov_b32_e32 v59, v0
	v_mov_b32_e32 v60, v0
	v_mov_b32_e32 v61, v0
	v_mov_b32_e32 v62, v0
	v_mov_b32_e32 v63, v0
	v_mov_b32_e32 v64, v0
	v_mov_b32_e32 v65, v0
	v_mov_b32_e32 v66, v0
	v_mov_b32_e32 v67, v0
	v_mov_b32_e32 v68, v0
	v_mov_b32_e32 v69, v0
	v_mov_b32_e32 v70, v0
	v_mov_b32_e32 v71, v0
	v_mov_b32_e32 v80, v0
	v_mov_b32_e32 v81, v0
	v_mov_b32_e32 v82, v0
	v_mov_b32_e32 v83, v0
	v_mov_b32_e32 v84, v0
	v_mov_b32_e32 v85, v0
	v_mov_b32_e32 v86, v0
	v_mov_b32_e32 v87, v0
	v_mov_b32_e32 v96, v0
	v_mov_b32_e32 v97, v0
	v_mov_b32_e32 v98, v0
	v_mov_b32_e32 v99, v0
	v_mov_b32_e32 v100, v0
	v_mov_b32_e32 v101, v0
	v_mov_b32_e32 v102, v0
	v_mov_b32_e32 v103, v0
	v_mov_b32_e32 v112, v0
	v_mov_b32_e32 v113, v0
	v_mov_b32_e32 v114, v0
	v_mov_b32_e32 v115, v0
	v_mov_b32_e32 v116, v0
	v_mov_b32_e32 v117, v0
	v_mov_b32_e32 v118, v0
	v_mov_b32_e32 v119, v0
	v_mov_b32_e32 v72, v0
	v_mov_b32_e32 v73, v0
	v_mov_b32_e32 v74, v0
	v_mov_b32_e32 v75, v0
	v_mov_b32_e32 v76, v0
	v_mov_b32_e32 v77, v0
	v_mov_b32_e32 v78, v0
	v_mov_b32_e32 v79, v0
	v_mov_b32_e32 v88, v0
	v_mov_b32_e32 v89, v0
	v_mov_b32_e32 v90, v0
	v_mov_b32_e32 v91, v0
	v_mov_b32_e32 v92, v0
	v_mov_b32_e32 v93, v0
	v_mov_b32_e32 v94, v0
	v_mov_b32_e32 v95, v0
	v_mov_b32_e32 v104, v0
	v_mov_b32_e32 v105, v0
	v_mov_b32_e32 v106, v0
	v_mov_b32_e32 v107, v0
	v_mov_b32_e32 v108, v0
	v_mov_b32_e32 v109, v0
	v_mov_b32_e32 v110, v0
	v_mov_b32_e32 v111, v0
	v_mov_b32_e32 v124, v0
	v_mov_b32_e32 v125, v0
	v_mov_b32_e32 v126, v0
	v_mov_b32_e32 v127, v0
	v_mov_b32_e32 v120, v0
	v_mov_b32_e32 v121, v0
	v_mov_b32_e32 v122, v0
	v_mov_b32_e32 v123, v0
	v_add_u32_e32 v232, s14, v171
	v_add_u32_e32 v233, s14, v145

; #define PG8_STAGE(bufoff, gbase, voff) do { _Pragma("unroll") for (int _i = 0; _i < 2; ++_i) { unsigned vo_ = (voff)[0]; asm volatile("" : "+v"(vo_));   \
;         __builtin_amdgcn_global_load_lds((const unsigned*)((const char*)(gbase) + (size_t)_i * r64step + vo_), (PG8_LAS unsigned*)(lds + (bufoff) + ldsw + _i * 8192), 16, 0, 0); } } while (0)
; #define PG8_WAIT_V(n) asm volatile("s_waitcnt vmcnt(" #n ")" ::: "memory")
; #define PG8_BAR __builtin_amdgcn_s_barrier()
; template <class Epi, class Sched, bool ALIGN_EPI = false, bool SP2 = false, bool F8 = false>
; __device__ __forceinline__ void gemm_phase(PG8_LAS unsigned char* lds, const Gemm g, const Sched& S, const Epi& E) {
;     ...
;     f32x4 acc[2][2][4][2];
; #pragma unroll
;     for (int a = 0; a < 2; ++a)
; #pragma unroll
;         for (int b = 0; b < 2; ++b)
; #pragma unroll
;             for (int m = 0; m < 4; ++m)
; #pragma unroll
;                 for (int n = 0; n < 2; ++n) acc[a][b][m][n] = (f32x4){0.f, 0.f, 0.f, 0.f};
;     bf16x8 At[4][2], B0[2][2], B1[2][2]; i32x8 At8[4], B08[2], B18[2];
;     const char* cA = (const char*)g.A + (size_t)cur.pm * tstep; const char* cB = (const char*)g.Bt + (size_t)cur.pn * tstep;
;     S.a_ready(cur);
;     if constexpr (SP2) {
;         PG8_STAGE(PG8_SB(0, 0), cB, voffB); PG8_STAGE(PG8_SB(0, 1), cB + hstep, voffB); PG8_STAGE(PG8_SA(0, 0), cA, voffA); PG8_STAGE(PG8_SA(0, 1), cA + hstep, voffA);
;         if (wr == 1) PG8_BAR;
;         PG8_WAIT_V(2); PG8_BAR;
;         PG8_STAGE(PG8_SB(1, 0), cB + kstep, voffB); PG8_STAGE(PG8_SA(1, 0), cA + kstep, voffA); PG8_STAGE(PG8_SB(1, 1), cB + hstep + kstep, voffB);
;         PG8_WAIT_V(6); PG8_BAR;
.LBB0_492:
	v_and_b32_e32 v175, 15, v174
	v_and_b32_e32 v0, 48, v174
	v_lshlrev_b32_e32 v1, 2, v174
	s_and_b32 s39, s47, 3
	s_lshl_b32 s44, s59, 13
	v_lshl_or_b32 v0, v175, 6, v0
	v_and_b32_e32 v1, 32, v1
	v_bitop3_b32 v2, v0, s44, v1 bitop3:0xde
	s_lshl_b32 s44, s39, 12
	v_mov_b32_e32 v148, v128
	v_bitop3_b32 v129, v0, s44, v1 bitop3:0xde
	s_waitcnt vmcnt(2)
	s_barrier
	s_add_i32 m0, s61, 0x18000
	v_lshl_add_u64 v[0:1], s[0:1], 0, v[148:149]
	v_lshl_add_u64 v[0:1], v[0:1], 0, s[20:21]
	v_mov_b32_e32 v148, v128
	global_load_lds_dwordx4 v[0:1], off
	s_add_i32 m0, s61, 0x1a000
	v_lshl_add_u64 v[0:1], s[0:1], 0, v[148:149]
	v_lshl_add_u64 v[0:1], v[0:1], 0, s[22:23]
	v_mov_b32_e32 v148, v128
	global_load_lds_dwordx4 v[0:1], off
	s_add_i32 s65, s61, 0x8000
	v_lshl_add_u64 v[0:1], s[6:7], 0, v[148:149]
	v_lshl_add_u64 v[0:1], v[0:1], 0, s[20:21]
	s_mov_b32 m0, s65
	v_mov_b32_e32 v148, v128
	global_load_lds_dwordx4 v[0:1], off
	s_add_i32 s66, s61, 0xa000
	v_lshl_add_u64 v[0:1], s[6:7], 0, v[148:149]
	v_lshl_add_u64 v[0:1], v[0:1], 0, s[22:23]
	s_mov_b32 m0, s66
	v_mov_b32_e32 v148, v128
	global_load_lds_dwordx4 v[0:1], off
	s_add_i32 m0, s61, 0x1c000
	v_lshl_add_u64 v[0:1], s[0:1], 0, v[148:149]
	v_lshl_add_u64 v[0:1], v[0:1], 0, s[24:25]
	v_mov_b32_e32 v148, v128
	global_load_lds_dwordx4 v[0:1], off
	s_add_i32 m0, s61, 0x1e000
	v_lshl_add_u64 v[0:1], s[0:1], 0, v[148:149]
	v_lshl_add_u64 v[0:1], v[0:1], 0, s[26:27]
	global_load_lds_dwordx4 v[0:1], off
	s_add_u32 s67, s96, s40
	s_waitcnt vmcnt(6)
	s_addc_u32 s68, s97, s41
	s_add_u32 s69, s49, s42
	v_lshl_or_b32 v153, s59, 6, v175
	s_addc_u32 s70, s50, s43
	s_mov_b32 s71, -2
	s_mov_b64 s[40:41], 0
	v_add_u32_e32 v130, 0, v2
	v_mov_b64_e32 v[104:105], 0
	v_mov_b64_e32 v[106:107], 0
	v_mov_b64_e32 v[0:1], 0
	v_mov_b64_e32 v[2:3], 0
	v_mov_b64_e32 v[112:113], 0
	v_mov_b64_e32 v[114:115], 0
	v_mov_b64_e32 v[12:13], 0
	v_mov_b64_e32 v[14:15], 0
	v_mov_b64_e32 v[120:121], 0
	v_mov_b64_e32 v[122:123], 0
	v_mov_b64_e32 v[36:37], 0
	v_mov_b64_e32 v[38:39], 0
	v_mov_b64_e32 v[124:125], 0
	v_mov_b64_e32 v[126:127], 0
	v_mov_b64_e32 v[56:57], 0
	v_mov_b64_e32 v[58:59], 0
	v_mov_b64_e32 v[8:9], 0
	v_mov_b64_e32 v[10:11], 0
	v_mov_b64_e32 v[28:29], 0
	v_mov_b64_e32 v[30:31], 0
	v_mov_b64_e32 v[24:25], 0
	v_mov_b64_e32 v[26:27], 0
	v_mov_b64_e32 v[44:45], 0
	v_mov_b64_e32 v[46:47], 0
	v_mov_b64_e32 v[48:49], 0
	v_mov_b64_e32 v[50:51], 0
	v_mov_b64_e32 v[88:89], 0
	v_mov_b64_e32 v[90:91], 0
	v_mov_b64_e32 v[68:69], 0
	v_mov_b64_e32 v[70:71], 0
	v_mov_b64_e32 v[92:93], 0
	v_mov_b64_e32 v[94:95], 0
	v_mov_b64_e32 v[96:97], 0
	v_mov_b64_e32 v[98:99], 0
	v_mov_b64_e32 v[4:5], 0
	v_mov_b64_e32 v[6:7], 0
	v_mov_b64_e32 v[100:101], 0
	v_mov_b64_e32 v[102:103], 0
	v_mov_b64_e32 v[20:21], 0
	v_mov_b64_e32 v[22:23], 0
	v_mov_b64_e32 v[108:109], 0
	v_mov_b64_e32 v[110:111], 0
	v_mov_b64_e32 v[40:41], 0
	v_mov_b64_e32 v[42:43], 0
	v_mov_b64_e32 v[116:117], 0
	v_mov_b64_e32 v[118:119], 0
	v_mov_b64_e32 v[72:73], 0
	v_mov_b64_e32 v[74:75], 0
	v_mov_b64_e32 v[16:17], 0
	v_mov_b64_e32 v[18:19], 0
	v_mov_b64_e32 v[60:61], 0
	v_mov_b64_e32 v[62:63], 0
	v_mov_b64_e32 v[32:33], 0
	v_mov_b64_e32 v[34:35], 0
	v_mov_b64_e32 v[64:65], 0
	v_mov_b64_e32 v[66:67], 0
	v_mov_b64_e32 v[52:53], 0
	v_mov_b64_e32 v[54:55], 0
	v_mov_b64_e32 v[76:77], 0
	v_mov_b64_e32 v[78:79], 0
	v_mov_b64_e32 v[84:85], 0
	v_mov_b64_e32 v[86:87], 0
	v_mov_b64_e32 v[80:81], 0
	v_mov_b64_e32 v[82:83], 0
	s_barrier
	v_add_u32_e32 v216, s28, v128
	v_add_u32_e32 v217, s30, v128
	v_add_u32_e32 v218, s14, v128
	v_add_u32_e32 v219, s16, v128
	v_add_u32_e32 v220, s18, v128
	v_add_u32_e32 v221, s20, v128
	v_add_u32_e32 v222, s22, v128
	v_add_u32_e32 v223, s24, v128
	v_add_u32_e32 v224, s26, v128
